# attention loop: stacked packed-mov accumulator init + second QK MFMA group hoisted above the first softmax (on top of v19)
# baseline (speedup 1.0000x reference)
; #define LAS __attribute__((address_space(3)))
; __device__ __forceinline__ f32x16 mfma32(bf16x8 a, bf16x8 b, f32x16 c) { return __builtin_amdgcn_mfma_f32_32x32x16_bf16(a, b, c, 0, 0, 0); }
; __device__ __forceinline__ void attn_item(PC p, int wv, int L, int item, LAS unsigned char* lds) {
;     ...
;         f32x16 st0;
;         bf16x8 kfa[4];
; #pragma unroll
;         for (int ks = 0; ks < 4; ++ks) kfa[ks] = *(const LAS bf16x8*)(Kb + j * 144 + ks * 32 + g * 16);
; #pragma unroll
;         for (int r = 0; r < 16; ++r) st0[r] = c0;
; #pragma unroll
;         for (int ks = 0; ks < 4; ++ks) st0 = mfma32(kfa[ks], Qf[ks], st0);
;     ...
; #pragma unroll
;         for (int ks = 0; ks < 4; ++ks) kfa[ks] = *(const LAS bf16x8*)(Kb + (32 + j) * 144 + ks * 32 + g * 16);
;         AT_SOFT(st0, 0, p0a, p0b)
; #pragma unroll
;         for (int r = 0; r < 16; ++r) st0[r] = c0;
; #pragma unroll
;         for (int ks = 0; ks < 4; ++ks) st0 = mfma32(kfa[ks], Qf[ks], st0);
.LBB0_332:
	s_bfe_u32 s12, s23, 0x70009
	s_mul_i32 s12, s12, 3
	s_sub_i32 s12, s22, s12
	s_and_b32 s12, s12, 0xff
	s_mul_i32 s12, s12, 0x9800
	v_add_u32_e32 v136, s12, v208
	ds_read_b128 v[120:123], v136
	ds_read_b128 v[124:127], v136 offset:32
	v_mov_b32_e32 v65, v64
	v_pk_mov_b32 v[66:67], v[64:65], v[64:65]
	v_pk_mov_b32 v[68:69], v[64:65], v[64:65]
	v_pk_mov_b32 v[70:71], v[64:65], v[64:65]
	v_pk_mov_b32 v[72:73], v[64:65], v[64:65]
	v_pk_mov_b32 v[74:75], v[64:65], v[64:65]
	v_pk_mov_b32 v[76:77], v[64:65], v[64:65]
	v_pk_mov_b32 v[78:79], v[64:65], v[64:65]
	s_cmp_lg_u32 s14, 0
	s_cselect_b64 s[12:13], -1, 0
	s_waitcnt lgkmcnt(1)
	v_mfma_f32_32x32x16_bf16 v[80:95], v[120:123], v[108:111], v[64:79]
	ds_read_b128 v[120:123], v136 offset:64
	ds_read_b128 v[214:217], v136 offset:96
	s_cmp_eq_u32 s14, 0
	s_waitcnt lgkmcnt(2)
	v_mfma_f32_32x32x16_bf16 v[80:95], v[124:127], v[104:107], v[80:95]
	s_waitcnt lgkmcnt(1)
	v_mfma_f32_32x32x16_bf16 v[80:95], v[120:123], v[100:103], v[80:95]
	ds_read_b128 v[132:135], v136 offset:4608
	ds_read_b128 v[128:131], v136 offset:4640
	ds_read_b128 v[124:127], v136 offset:4672
	ds_read_b128 v[120:123], v136 offset:4704
	s_waitcnt lgkmcnt(4)
	v_mfma_f32_32x32x16_bf16 v[80:95], v[214:217], v[96:99], v[80:95]
	s_waitcnt lgkmcnt(3)
	v_mfma_f32_32x32x16_bf16 v[64:79], v[132:135], v[108:111], v[64:79]
	s_waitcnt lgkmcnt(2)
	v_mfma_f32_32x32x16_bf16 v[64:79], v[128:131], v[104:107], v[64:79]
	s_waitcnt lgkmcnt(1)
	v_mfma_f32_32x32x16_bf16 v[64:79], v[124:127], v[100:103], v[64:79]
	s_waitcnt lgkmcnt(0)
	v_mfma_f32_32x32x16_bf16 v[64:79], v[120:123], v[96:99], v[64:79]
	s_cbranch_scc1 .LBB0_354
	s_nop 2
	v_exp_f32_e32 v136, v80
	v_exp_f32_e32 v214, v81
	v_exp_f32_e32 v215, v82
	v_exp_f32_e32 v216, v83
	v_exp_f32_e32 v217, v84
	v_exp_f32_e32 v218, v85
	v_exp_f32_e32 v219, v86
	v_exp_f32_e32 v220, v87
	v_exp_f32_e32 v221, v88
	v_exp_f32_e32 v222, v89
	v_exp_f32_e32 v223, v90
	v_exp_f32_e32 v224, v91
	v_exp_f32_e32 v225, v92
	v_exp_f32_e32 v226, v93
	v_exp_f32_e32 v227, v94
	s_cbranch_execnz .LBB0_335

; __device__ __forceinline__ f32x16 mfma32(bf16x8 a, bf16x8 b, f32x16 c) { return __builtin_amdgcn_mfma_f32_32x32x16_bf16(a, b, c, 0, 0, 0); }
; __device__ __forceinline__ void attn_item(PC p, int wv, int L, int item, LAS unsigned char* lds) {
;     ...
;         AT_SOFT(st0, 0, p0a, p0b)
; #pragma unroll
;         for (int r = 0; r < 16; ++r) st0[r] = c0;
; #pragma unroll
;         for (int ks = 0; ks < 4; ++ks) st0 = mfma32(kfa[ks], Qf[ks], st0);
;         AT_SOFT(st0, 1, p1a, p1b)
.LBB0_335:
	s_andn2_b64 vcc, exec, s[12:13]
	s_cbranch_vccnz .LBB0_355
	v_exp_f32_e32 v80, v64
	v_exp_f32_e32 v81, v65
	v_exp_f32_e32 v82, v66
	v_exp_f32_e32 v83, v67
	v_exp_f32_e32 v84, v68
	v_exp_f32_e32 v85, v69
	v_exp_f32_e32 v86, v70
	v_exp_f32_e32 v87, v71
	v_exp_f32_e32 v88, v72
	v_exp_f32_e32 v89, v73
	v_exp_f32_e32 v90, v74
	v_exp_f32_e32 v91, v75
	v_exp_f32_e32 v92, v76
	v_exp_f32_e32 v93, v77
	v_exp_f32_e32 v94, v78
	s_cbranch_execnz .LBB0_338

; #define LAS __attribute__((address_space(3)))
; __device__ __forceinline__ f32x16 mfma32(bf16x8 a, bf16x8 b, f32x16 c) { return __builtin_amdgcn_mfma_f32_32x32x16_bf16(a, b, c, 0, 0, 0); }
; __device__ __forceinline__ void attn_item(PC p, int wv, int L, int item, LAS unsigned char* lds) {
;     ...
;         f32x16 st0;
;         bf16x8 kfa[4];
; #pragma unroll
;         for (int ks = 0; ks < 4; ++ks) kfa[ks] = *(const LAS bf16x8*)(Kb + j * 144 + ks * 32 + g * 16);
; #pragma unroll
;         for (int r = 0; r < 16; ++r) st0[r] = c0;
; #pragma unroll
;         for (int ks = 0; ks < 4; ++ks) st0 = mfma32(kfa[ks], Qf[ks], st0);
;     ...
; #pragma unroll
;         for (int ks = 0; ks < 4; ++ks) kfa[ks] = *(const LAS bf16x8*)(Kb + (32 + j) * 144 + ks * 32 + g * 16);
;         AT_SOFT(st0, 0, p0a, p0b)
; #pragma unroll
;         for (int r = 0; r < 16; ++r) st0[r] = c0;
; #pragma unroll
;         for (int ks = 0; ks < 4; ++ks) st0 = mfma32(kfa[ks], Qf[ks], st0);
.LBB0_345:
	s_bfe_u32 s12, s23, 0x70009
	s_mul_i32 s12, s12, 3
	s_sub_i32 s12, s22, s12
	s_and_b32 s12, s12, 0xff
	s_mul_i32 s12, s12, 0x9800
	v_add_u32_e32 v136, s12, v208
	ds_read_b128 v[112:115], v136
	ds_read_b128 v[116:119], v136 offset:32
	v_mov_b32_e32 v65, v64
	v_pk_mov_b32 v[66:67], v[64:65], v[64:65]
	v_pk_mov_b32 v[68:69], v[64:65], v[64:65]
	v_pk_mov_b32 v[70:71], v[64:65], v[64:65]
	v_pk_mov_b32 v[72:73], v[64:65], v[64:65]
	v_pk_mov_b32 v[74:75], v[64:65], v[64:65]
	v_pk_mov_b32 v[76:77], v[64:65], v[64:65]
	v_pk_mov_b32 v[78:79], v[64:65], v[64:65]
	s_cmp_lg_u32 s14, 0
	s_cselect_b64 s[12:13], -1, 0
	s_waitcnt lgkmcnt(1)
	v_mfma_f32_32x32x16_bf16 v[80:95], v[112:115], v[108:111], v[64:79]
	ds_read_b128 v[112:115], v136 offset:64
	ds_read_b128 v[214:217], v136 offset:96
	s_cmp_eq_u32 s14, 0
	s_waitcnt lgkmcnt(2)
	v_mfma_f32_32x32x16_bf16 v[80:95], v[116:119], v[104:107], v[80:95]
	s_waitcnt lgkmcnt(1)
	v_mfma_f32_32x32x16_bf16 v[80:95], v[112:115], v[100:103], v[80:95]
	ds_read_b128 v[132:135], v136 offset:4608
	ds_read_b128 v[128:131], v136 offset:4640
	ds_read_b128 v[116:119], v136 offset:4672
	ds_read_b128 v[112:115], v136 offset:4704
	s_waitcnt lgkmcnt(4)
	v_mfma_f32_32x32x16_bf16 v[80:95], v[214:217], v[96:99], v[80:95]
	s_waitcnt lgkmcnt(3)
	v_mfma_f32_32x32x16_bf16 v[64:79], v[132:135], v[108:111], v[64:79]
	s_waitcnt lgkmcnt(2)
	v_mfma_f32_32x32x16_bf16 v[64:79], v[128:131], v[104:107], v[64:79]
	s_waitcnt lgkmcnt(1)
	v_mfma_f32_32x32x16_bf16 v[64:79], v[116:119], v[100:103], v[64:79]
	s_waitcnt lgkmcnt(0)
	v_mfma_f32_32x32x16_bf16 v[64:79], v[112:115], v[96:99], v[64:79]
	s_cbranch_scc1 .LBB0_356
	s_nop 2
	v_exp_f32_e32 v136, v80
	v_exp_f32_e32 v214, v81
	v_exp_f32_e32 v215, v82
	v_exp_f32_e32 v216, v83
	v_exp_f32_e32 v217, v84
	v_exp_f32_e32 v218, v85
	v_exp_f32_e32 v219, v86
	v_exp_f32_e32 v220, v87
	v_exp_f32_e32 v221, v88
	v_exp_f32_e32 v222, v89
	v_exp_f32_e32 v223, v90
	v_exp_f32_e32 v224, v91
	v_exp_f32_e32 v225, v92
	v_exp_f32_e32 v227, v93
	v_exp_f32_e32 v228, v94
	v_add_u32_e32 v226, s21, v213
	s_cbranch_execnz .LBB0_348

; #define LAS __attribute__((address_space(3)))
; __device__ __forceinline__ f32x16 mfma32(bf16x8 a, bf16x8 b, f32x16 c) { return __builtin_amdgcn_mfma_f32_32x32x16_bf16(a, b, c, 0, 0, 0); }
; __device__ __forceinline__ void attn_item(PC p, int wv, int L, int item, LAS unsigned char* lds) {
;     ...
;         f32x16 st0;
;         bf16x8 kfa[4];
; #pragma unroll
;         for (int ks = 0; ks < 4; ++ks) kfa[ks] = *(const LAS bf16x8*)(Kb + j * 144 + ks * 32 + g * 16);
; #pragma unroll
;         for (int r = 0; r < 16; ++r) st0[r] = c0;
; #pragma unroll
;         for (int ks = 0; ks < 4; ++ks) st0 = mfma32(kfa[ks], Qf[ks], st0);
.LBB0_375:
	s_cmpk_gt_u32 s18, 0x1f21
	s_cselect_b64 s[10:11], -1, 0
	s_cmpk_lt_u32 s18, 0x1f22
	ds_read_b128 v[112:115], v208 offset:38912
	ds_read_b128 v[116:119], v208 offset:38944
	s_cselect_b64 vcc, -1, 0
	v_cndmask_b32_e32 v64, 0, v207, vcc
	v_mov_b32_e32 v65, v64
	v_pk_mov_b32 v[66:67], v[64:65], v[64:65]
	v_pk_mov_b32 v[68:69], v[64:65], v[64:65]
	v_pk_mov_b32 v[70:71], v[64:65], v[64:65]
	v_pk_mov_b32 v[72:73], v[64:65], v[64:65]
	v_pk_mov_b32 v[74:75], v[64:65], v[64:65]
	v_pk_mov_b32 v[76:77], v[64:65], v[64:65]
	v_pk_mov_b32 v[78:79], v[64:65], v[64:65]
	s_and_b64 vcc, exec, s[10:11]
	s_waitcnt lgkmcnt(1)
	v_mfma_f32_32x32x16_bf16 v[80:95], v[112:115], v[108:111], v[64:79]
	ds_read_b128 v[112:115], v208 offset:38976
	ds_read_b128 v[128:131], v208 offset:39008
	s_waitcnt lgkmcnt(2)
	v_mfma_f32_32x32x16_bf16 v[80:95], v[116:119], v[104:107], v[80:95]
	s_waitcnt lgkmcnt(1)
	v_mfma_f32_32x32x16_bf16 v[80:95], v[112:115], v[100:103], v[80:95]
	ds_read_b128 v[124:127], v208 offset:43520
	ds_read_b128 v[120:123], v208 offset:43552
	ds_read_b128 v[116:119], v208 offset:43584
	ds_read_b128 v[112:115], v208 offset:43616
	s_waitcnt lgkmcnt(4)
	v_mfma_f32_32x32x16_bf16 v[80:95], v[128:131], v[96:99], v[80:95]
	s_cbranch_vccz .LBB0_418
	s_sub_i32 s12, 0x1fc0, s18
	v_add_u32_e32 v128, s12, v206
	v_add_u32_e32 v129, s12, v205
	v_add_u32_e32 v130, s12, v204
	v_add_u32_e32 v131, s12, v203
	v_add_u32_e32 v132, s12, v202
	v_add_u32_e32 v133, s12, v201
	v_add_u32_e32 v134, s12, v200
	v_add_u32_e32 v135, s12, v199
	v_med3_i32 v128, v128, s82, v156
	v_med3_i32 v129, v129, s82, v156
	v_med3_i32 v130, v130, s82, v156
	v_med3_i32 v131, v131, s82, v156
	v_med3_i32 v132, v132, s82, v156
	v_med3_i32 v133, v133, s82, v156
	v_med3_i32 v134, v134, s82, v156
	v_med3_i32 v135, v135, s82, v156
	v_add_u32_e32 v136, s12, v198
	v_add_u32_e32 v140, s12, v197
	v_add_u32_e32 v142, s12, v196
	v_add_u32_e32 v144, s12, v195
	v_add_u32_e32 v145, s12, v194
	v_add_u32_e32 v146, s12, v193
	v_add_u32_e32 v147, s12, v192
	v_add_u32_e32 v148, s12, v191
	v_lshl_add_u32 v128, v128, 2, s17
	v_lshl_add_u32 v129, v129, 2, s17
	v_lshl_add_u32 v130, v130, 2, s17
	v_lshl_add_u32 v131, v131, 2, s17
	v_lshl_add_u32 v132, v132, 2, s17
	v_lshl_add_u32 v133, v133, 2, s17
	v_lshl_add_u32 v134, v134, 2, s17
	v_lshl_add_u32 v135, v135, 2, s17
	v_med3_i32 v136, v136, s82, v156
	v_med3_i32 v140, v140, s82, v156
	v_med3_i32 v142, v142, s82, v156
	v_med3_i32 v144, v144, s82, v156
	v_med3_i32 v145, v145, s82, v156
	v_med3_i32 v146, v146, s82, v156
	v_med3_i32 v147, v147, s82, v156
	v_med3_i32 v148, v148, s82, v156
	ds_read_b32 v128, v128 offset:512
	ds_read_b32 v129, v129 offset:512
	ds_read_b32 v130, v130 offset:512
	ds_read_b32 v131, v131 offset:512
	ds_read_b32 v132, v132 offset:512
	ds_read_b32 v133, v133 offset:512
	ds_read_b32 v134, v134 offset:512
	ds_read_b32 v135, v135 offset:512
	v_lshl_add_u32 v136, v136, 2, s17
	v_lshl_add_u32 v140, v140, 2, s17
	v_lshl_add_u32 v142, v142, 2, s17
	v_lshl_add_u32 v144, v144, 2, s17
	v_lshl_add_u32 v145, v145, 2, s17
	v_lshl_add_u32 v146, v146, 2, s17
	v_lshl_add_u32 v147, v147, 2, s17
	v_lshl_add_u32 v148, v148, 2, s17
	ds_read_b32 v136, v136 offset:512
	ds_read_b32 v140, v140 offset:512
	ds_read_b32 v142, v142 offset:512
	ds_read_b32 v144, v144 offset:512
	ds_read_b32 v145, v145 offset:512
	ds_read_b32 v146, v146 offset:512
	ds_read_b32 v147, v147 offset:512
	ds_read_b32 v148, v148 offset:512
	s_waitcnt lgkmcnt(14)
	v_add_f32_e32 v128, v80, v128
	v_add_f32_e32 v129, v81, v129
	s_waitcnt lgkmcnt(13)
	v_add_f32_e32 v130, v82, v130
	s_waitcnt lgkmcnt(12)
	v_add_f32_e32 v131, v83, v131
	s_waitcnt lgkmcnt(11)
	v_add_f32_e32 v132, v84, v132
	s_waitcnt lgkmcnt(10)
	v_add_f32_e32 v133, v85, v133
	s_waitcnt lgkmcnt(9)
	v_add_f32_e32 v134, v86, v134
	s_waitcnt lgkmcnt(8)
	v_add_f32_e32 v135, v87, v135
	s_waitcnt lgkmcnt(7)
	v_add_f32_e32 v136, v88, v136
	s_waitcnt lgkmcnt(6)
	v_add_f32_e32 v140, v89, v140
	s_waitcnt lgkmcnt(5)
	v_add_f32_e32 v142, v90, v142
	s_waitcnt lgkmcnt(4)
	v_add_f32_e32 v144, v91, v144
	s_waitcnt lgkmcnt(3)
	v_add_f32_e32 v145, v92, v145
	s_waitcnt lgkmcnt(2)
	v_add_f32_e32 v146, v93, v146
	s_waitcnt lgkmcnt(1)
	v_add_f32_e32 v147, v94, v147
	v_exp_f32_e32 v128, v128
	v_exp_f32_e32 v129, v129
	v_exp_f32_e32 v130, v130
	v_exp_f32_e32 v131, v131
	v_exp_f32_e32 v132, v132
	v_exp_f32_e32 v133, v133
	v_exp_f32_e32 v134, v134
	v_exp_f32_e32 v135, v135
	v_exp_f32_e32 v136, v136
	v_exp_f32_e32 v140, v140
	v_exp_f32_e32 v142, v142
	v_exp_f32_e32 v144, v144
	v_exp_f32_e32 v145, v145
	v_exp_f32_e32 v146, v146
	v_exp_f32_e32 v147, v147
	s_waitcnt lgkmcnt(0)
	v_add_f32_e32 v95, v95, v148
	s_cbranch_execz .LBB0_419
	s_branch .LBB0_420

; #define LAS __attribute__((address_space(3)))
; __device__ __forceinline__ f32x16 mfma32(bf16x8 a, bf16x8 b, f32x16 c) { return __builtin_amdgcn_mfma_f32_32x32x16_bf16(a, b, c, 0, 0, 0); }
; __device__ __forceinline__ void attn_item(PC p, int wv, int L, int item, LAS unsigned char* lds) {
;     ...
;         f32x16 st0;
;         bf16x8 kfa[4];
; #pragma unroll
;         for (int ks = 0; ks < 4; ++ks) kfa[ks] = *(const LAS bf16x8*)(Kb + j * 144 + ks * 32 + g * 16);
; #pragma unroll
;         for (int r = 0; r < 16; ++r) st0[r] = c0;
; #pragma unroll
;         for (int ks = 0; ks < 4; ++ks) st0 = mfma32(kfa[ks], Qf[ks], st0);
;     ...
; #pragma unroll
;         for (int ks = 0; ks < 4; ++ks) kfa[ks] = *(const LAS bf16x8*)(Kb + (32 + j) * 144 + ks * 32 + g * 16);
;         AT_SOFT(st0, 0, p0a, p0b)
; #pragma unroll
;         for (int r = 0; r < 16; ++r) st0[r] = c0;
; #pragma unroll
;         for (int ks = 0; ks < 4; ++ks) st0 = mfma32(kfa[ks], Qf[ks], st0);
.LBB0_1007:
	s_bfe_u32 s12, s22, 0x70009
	s_mul_i32 s12, s12, 3
	s_sub_i32 s12, s21, s12
	s_and_b32 s12, s12, 0xff
	s_mul_i32 s12, s12, 0x9800
	v_add_u32_e32 v136, s12, v210
	ds_read_b128 v[120:123], v136
	ds_read_b128 v[124:127], v136 offset:32
	v_mov_b32_e32 v65, v64
	v_pk_mov_b32 v[66:67], v[64:65], v[64:65]
	v_pk_mov_b32 v[68:69], v[64:65], v[64:65]
	v_pk_mov_b32 v[70:71], v[64:65], v[64:65]
	v_pk_mov_b32 v[72:73], v[64:65], v[64:65]
	v_pk_mov_b32 v[74:75], v[64:65], v[64:65]
	v_pk_mov_b32 v[76:77], v[64:65], v[64:65]
	v_pk_mov_b32 v[78:79], v[64:65], v[64:65]
	s_cmp_lg_u32 s14, 0
	s_cselect_b64 s[12:13], -1, 0
	s_waitcnt lgkmcnt(1)
	v_mfma_f32_32x32x16_bf16 v[80:95], v[120:123], v[108:111], v[64:79]
	ds_read_b128 v[120:123], v136 offset:64
	ds_read_b128 v[216:219], v136 offset:96
	s_cmp_eq_u32 s14, 0
	s_waitcnt lgkmcnt(2)
	v_mfma_f32_32x32x16_bf16 v[80:95], v[124:127], v[104:107], v[80:95]
	s_waitcnt lgkmcnt(1)
	v_mfma_f32_32x32x16_bf16 v[80:95], v[120:123], v[100:103], v[80:95]
	ds_read_b128 v[132:135], v136 offset:4608
	ds_read_b128 v[128:131], v136 offset:4640
	ds_read_b128 v[124:127], v136 offset:4672
	ds_read_b128 v[120:123], v136 offset:4704
	s_waitcnt lgkmcnt(4)
	v_mfma_f32_32x32x16_bf16 v[80:95], v[216:219], v[96:99], v[80:95]
	s_waitcnt lgkmcnt(3)
	v_mfma_f32_32x32x16_bf16 v[64:79], v[132:135], v[108:111], v[64:79]
	s_waitcnt lgkmcnt(2)
	v_mfma_f32_32x32x16_bf16 v[64:79], v[128:131], v[104:107], v[64:79]
	s_waitcnt lgkmcnt(1)
	v_mfma_f32_32x32x16_bf16 v[64:79], v[124:127], v[100:103], v[64:79]
	s_waitcnt lgkmcnt(0)
	v_mfma_f32_32x32x16_bf16 v[64:79], v[120:123], v[96:99], v[64:79]
	s_cbranch_scc1 .LBB0_1029
	s_nop 2
	v_exp_f32_e32 v136, v80
	v_exp_f32_e32 v216, v81
	v_exp_f32_e32 v217, v82
	v_exp_f32_e32 v218, v83
	v_exp_f32_e32 v219, v84
	v_exp_f32_e32 v220, v85
	v_exp_f32_e32 v221, v86
	v_exp_f32_e32 v222, v87
	v_exp_f32_e32 v223, v88
	v_exp_f32_e32 v224, v89
	v_exp_f32_e32 v225, v90
	v_exp_f32_e32 v226, v91
	v_exp_f32_e32 v227, v92
	v_exp_f32_e32 v228, v93
	v_exp_f32_e32 v229, v94
	s_cbranch_execnz .LBB0_1010

; #define LAS __attribute__((address_space(3)))
; __device__ __forceinline__ f32x16 mfma32(bf16x8 a, bf16x8 b, f32x16 c) { return __builtin_amdgcn_mfma_f32_32x32x16_bf16(a, b, c, 0, 0, 0); }
; __device__ __forceinline__ void attn_item(PC p, int wv, int L, int item, LAS unsigned char* lds) {
;     ...
;         f32x16 st0;
;         bf16x8 kfa[4];
; #pragma unroll
;         for (int ks = 0; ks < 4; ++ks) kfa[ks] = *(const LAS bf16x8*)(Kb + j * 144 + ks * 32 + g * 16);
; #pragma unroll
;         for (int r = 0; r < 16; ++r) st0[r] = c0;
; #pragma unroll
;         for (int ks = 0; ks < 4; ++ks) st0 = mfma32(kfa[ks], Qf[ks], st0);
;     ...
; #pragma unroll
;         for (int ks = 0; ks < 4; ++ks) kfa[ks] = *(const LAS bf16x8*)(Kb + (32 + j) * 144 + ks * 32 + g * 16);
;         AT_SOFT(st0, 0, p0a, p0b)
; #pragma unroll
;         for (int r = 0; r < 16; ++r) st0[r] = c0;
; #pragma unroll
;         for (int ks = 0; ks < 4; ++ks) st0 = mfma32(kfa[ks], Qf[ks], st0);
.LBB0_1020:
	s_bfe_u32 s12, s22, 0x70009
	s_mul_i32 s12, s12, 3
	s_sub_i32 s12, s21, s12
	s_and_b32 s12, s12, 0xff
	s_mul_i32 s12, s12, 0x9800
	v_add_u32_e32 v136, s12, v210
	ds_read_b128 v[112:115], v136
	ds_read_b128 v[116:119], v136 offset:32
	v_mov_b32_e32 v65, v64
	v_pk_mov_b32 v[66:67], v[64:65], v[64:65]
	v_pk_mov_b32 v[68:69], v[64:65], v[64:65]
	v_pk_mov_b32 v[70:71], v[64:65], v[64:65]
	v_pk_mov_b32 v[72:73], v[64:65], v[64:65]
	v_pk_mov_b32 v[74:75], v[64:65], v[64:65]
	v_pk_mov_b32 v[76:77], v[64:65], v[64:65]
	v_pk_mov_b32 v[78:79], v[64:65], v[64:65]
	s_cmp_lg_u32 s14, 0
	s_cselect_b64 s[12:13], -1, 0
	s_waitcnt lgkmcnt(1)
	v_mfma_f32_32x32x16_bf16 v[80:95], v[112:115], v[108:111], v[64:79]
	ds_read_b128 v[112:115], v136 offset:64
	ds_read_b128 v[216:219], v136 offset:96
	s_cmp_eq_u32 s14, 0
	s_waitcnt lgkmcnt(2)
	v_mfma_f32_32x32x16_bf16 v[80:95], v[116:119], v[104:107], v[80:95]
	s_waitcnt lgkmcnt(1)
	v_mfma_f32_32x32x16_bf16 v[80:95], v[112:115], v[100:103], v[80:95]
	ds_read_b128 v[132:135], v136 offset:4608
	ds_read_b128 v[128:131], v136 offset:4640
	ds_read_b128 v[116:119], v136 offset:4672
	ds_read_b128 v[112:115], v136 offset:4704
	s_waitcnt lgkmcnt(4)
	v_mfma_f32_32x32x16_bf16 v[80:95], v[216:219], v[96:99], v[80:95]
	s_waitcnt lgkmcnt(3)
	v_mfma_f32_32x32x16_bf16 v[64:79], v[132:135], v[108:111], v[64:79]
	s_waitcnt lgkmcnt(2)
	v_mfma_f32_32x32x16_bf16 v[64:79], v[128:131], v[104:107], v[64:79]
	s_waitcnt lgkmcnt(1)
	v_mfma_f32_32x32x16_bf16 v[64:79], v[116:119], v[100:103], v[64:79]
	s_waitcnt lgkmcnt(0)
	v_mfma_f32_32x32x16_bf16 v[64:79], v[112:115], v[96:99], v[64:79]
	s_cbranch_scc1 .LBB0_1031
	s_nop 2
	v_exp_f32_e32 v136, v80
	v_exp_f32_e32 v216, v81
	v_exp_f32_e32 v217, v82
	v_exp_f32_e32 v218, v83
	v_exp_f32_e32 v219, v84
	v_exp_f32_e32 v220, v85
	v_exp_f32_e32 v221, v86
	v_exp_f32_e32 v222, v87
	v_exp_f32_e32 v223, v88
	v_exp_f32_e32 v224, v89
	v_exp_f32_e32 v225, v90
	v_exp_f32_e32 v226, v91
	v_exp_f32_e32 v227, v92
	v_exp_f32_e32 v229, v93
	v_exp_f32_e32 v230, v94
	v_add_u32_e32 v228, s20, v215
	s_cbranch_execnz .LBB0_1023

; #define LAS __attribute__((address_space(3)))
; __device__ __forceinline__ f32x16 mfma32(bf16x8 a, bf16x8 b, f32x16 c) { return __builtin_amdgcn_mfma_f32_32x32x16_bf16(a, b, c, 0, 0, 0); }
; __device__ __forceinline__ void attn_item(PC p, int wv, int L, int item, LAS unsigned char* lds) {
;     ...
;         f32x16 st0;
;         bf16x8 kfa[4];
; #pragma unroll
;         for (int ks = 0; ks < 4; ++ks) kfa[ks] = *(const LAS bf16x8*)(Kb + j * 144 + ks * 32 + g * 16);
; #pragma unroll
;         for (int r = 0; r < 16; ++r) st0[r] = c0;
; #pragma unroll
;         for (int ks = 0; ks < 4; ++ks) st0 = mfma32(kfa[ks], Qf[ks], st0);
.LBB0_1050:
	s_cmpk_gt_u32 s17, 0x1f21
	s_cselect_b64 s[10:11], -1, 0
	s_cmpk_lt_u32 s17, 0x1f22
	ds_read_b128 v[112:115], v210 offset:38912
	ds_read_b128 v[116:119], v210 offset:38944
	s_cselect_b64 vcc, -1, 0
	v_cndmask_b32_e32 v64, 0, v209, vcc
	v_mov_b32_e32 v65, v64
	v_pk_mov_b32 v[66:67], v[64:65], v[64:65]
	v_pk_mov_b32 v[68:69], v[64:65], v[64:65]
	v_pk_mov_b32 v[70:71], v[64:65], v[64:65]
	v_pk_mov_b32 v[72:73], v[64:65], v[64:65]
	v_pk_mov_b32 v[74:75], v[64:65], v[64:65]
	v_pk_mov_b32 v[76:77], v[64:65], v[64:65]
	v_pk_mov_b32 v[78:79], v[64:65], v[64:65]
	s_and_b64 vcc, exec, s[10:11]
	s_waitcnt lgkmcnt(1)
	v_mfma_f32_32x32x16_bf16 v[80:95], v[112:115], v[108:111], v[64:79]
	ds_read_b128 v[112:115], v210 offset:38976
	ds_read_b128 v[128:131], v210 offset:39008
	s_waitcnt lgkmcnt(2)
	v_mfma_f32_32x32x16_bf16 v[80:95], v[116:119], v[104:107], v[80:95]
	s_waitcnt lgkmcnt(1)
	v_mfma_f32_32x32x16_bf16 v[80:95], v[112:115], v[100:103], v[80:95]
	ds_read_b128 v[124:127], v210 offset:43520
	ds_read_b128 v[120:123], v210 offset:43552
	ds_read_b128 v[116:119], v210 offset:43584
	ds_read_b128 v[112:115], v210 offset:43616
	s_waitcnt lgkmcnt(4)
	v_mfma_f32_32x32x16_bf16 v[80:95], v[128:131], v[96:99], v[80:95]
	s_cbranch_vccz .LBB0_1093
	s_sub_i32 s12, 0x1fc0, s17
	v_add_u32_e32 v128, s12, v208
	v_add_u32_e32 v129, s12, v207
	v_add_u32_e32 v130, s12, v206
	v_add_u32_e32 v131, s12, v205
	v_add_u32_e32 v132, s12, v204
	v_add_u32_e32 v133, s12, v203
	v_add_u32_e32 v134, s12, v202
	v_add_u32_e32 v135, s12, v201
	v_med3_i32 v128, v128, s52, v158
	v_med3_i32 v129, v129, s52, v158
	v_med3_i32 v130, v130, s52, v158
	v_med3_i32 v131, v131, s52, v158
	v_med3_i32 v132, v132, s52, v158
	v_med3_i32 v133, v133, s52, v158
	v_med3_i32 v134, v134, s52, v158
	v_med3_i32 v135, v135, s52, v158
	v_add_u32_e32 v136, s12, v200
	v_add_u32_e32 v140, s12, v199
	v_add_u32_e32 v142, s12, v198
	v_add_u32_e32 v144, s12, v197
	v_add_u32_e32 v145, s12, v196
	v_add_u32_e32 v146, s12, v195
	v_add_u32_e32 v147, s12, v194
	v_add_u32_e32 v148, s12, v193
	v_lshl_add_u32 v128, v128, 2, s84
	v_lshl_add_u32 v129, v129, 2, s84
	v_lshl_add_u32 v130, v130, 2, s84
	v_lshl_add_u32 v131, v131, 2, s84
	v_lshl_add_u32 v132, v132, 2, s84
	v_lshl_add_u32 v133, v133, 2, s84
	v_lshl_add_u32 v134, v134, 2, s84
	v_lshl_add_u32 v135, v135, 2, s84
	v_med3_i32 v136, v136, s52, v158
	v_med3_i32 v140, v140, s52, v158
	v_med3_i32 v142, v142, s52, v158
	v_med3_i32 v144, v144, s52, v158
	v_med3_i32 v145, v145, s52, v158
	v_med3_i32 v146, v146, s52, v158
	v_med3_i32 v147, v147, s52, v158
	v_med3_i32 v148, v148, s52, v158
	ds_read_b32 v128, v128 offset:512
	ds_read_b32 v129, v129 offset:512
	ds_read_b32 v130, v130 offset:512
	ds_read_b32 v131, v131 offset:512
	ds_read_b32 v132, v132 offset:512
	ds_read_b32 v133, v133 offset:512
	ds_read_b32 v134, v134 offset:512
	ds_read_b32 v135, v135 offset:512
	v_lshl_add_u32 v136, v136, 2, s84
	v_lshl_add_u32 v140, v140, 2, s84
	v_lshl_add_u32 v142, v142, 2, s84
	v_lshl_add_u32 v144, v144, 2, s84
	v_lshl_add_u32 v145, v145, 2, s84
	v_lshl_add_u32 v146, v146, 2, s84
	v_lshl_add_u32 v147, v147, 2, s84
	v_lshl_add_u32 v148, v148, 2, s84
	ds_read_b32 v136, v136 offset:512
	ds_read_b32 v140, v140 offset:512
	ds_read_b32 v142, v142 offset:512
	ds_read_b32 v144, v144 offset:512
	ds_read_b32 v145, v145 offset:512
	ds_read_b32 v146, v146 offset:512
	ds_read_b32 v147, v147 offset:512
	ds_read_b32 v148, v148 offset:512
	s_waitcnt lgkmcnt(14)
	v_add_f32_e32 v128, v80, v128
	v_add_f32_e32 v129, v81, v129
	s_waitcnt lgkmcnt(13)
	v_add_f32_e32 v130, v82, v130
	s_waitcnt lgkmcnt(12)
	v_add_f32_e32 v131, v83, v131
	s_waitcnt lgkmcnt(11)
	v_add_f32_e32 v132, v84, v132
	s_waitcnt lgkmcnt(10)
	v_add_f32_e32 v133, v85, v133
	s_waitcnt lgkmcnt(9)
	v_add_f32_e32 v134, v86, v134
	s_waitcnt lgkmcnt(8)
	v_add_f32_e32 v135, v87, v135
	s_waitcnt lgkmcnt(7)
	v_add_f32_e32 v136, v88, v136
	s_waitcnt lgkmcnt(6)
	v_add_f32_e32 v140, v89, v140
	s_waitcnt lgkmcnt(5)
	v_add_f32_e32 v142, v90, v142
	s_waitcnt lgkmcnt(4)
	v_add_f32_e32 v144, v91, v144
	s_waitcnt lgkmcnt(3)
	v_add_f32_e32 v145, v92, v145
	s_waitcnt lgkmcnt(2)
	v_add_f32_e32 v146, v93, v146
	s_waitcnt lgkmcnt(1)
	v_add_f32_e32 v147, v94, v147
	v_exp_f32_e32 v128, v128
	v_exp_f32_e32 v129, v129
	v_exp_f32_e32 v130, v130
	v_exp_f32_e32 v131, v131
	v_exp_f32_e32 v132, v132
	v_exp_f32_e32 v133, v133
	v_exp_f32_e32 v134, v134
	v_exp_f32_e32 v135, v135
	v_exp_f32_e32 v136, v136
	v_exp_f32_e32 v140, v140
	v_exp_f32_e32 v142, v142
	v_exp_f32_e32 v144, v144
	v_exp_f32_e32 v145, v145
	v_exp_f32_e32 v146, v146
	v_exp_f32_e32 v147, v147
	s_waitcnt lgkmcnt(0)
	v_add_f32_e32 v95, v95, v148
	s_cbranch_execz .LBB0_1094
	s_branch .LBB0_1095
